# attn_out / four_out GEMM epilogues (gate-multiply): paired gate/partial-sum loads of each output row issued together into free fragment registers with counted vmcnt
# baseline (speedup 1.0000x reference)
.LBB0_1312:
	v_lshl_add_u32 v140, s5, 8, v143
	v_lshl_or_b32 v138, s4, 8, v145
	v_ashrrev_i32_e32 v141, 31, v140
	v_lshlrev_b64 v[148:149], 12, v[140:141]
	v_ashrrev_i32_e32 v139, 31, v138
	v_lshl_add_u64 v[148:149], s[10:11], 0, v[148:149]
	v_lshlrev_b64 v[138:139], 1, v[138:139]
	v_lshl_add_u64 v[154:155], v[148:149], 0, v[138:139]
	global_load_dwordx4 v[160:163], v[154:155], off
	global_load_dwordx4 v[164:167], v[154:155], off offset:256
	v_lshlrev_b64 v[152:153], 11, v[140:141]
	s_mov_b64 s[0:1], -1
	s_andn2_b64 vcc, exec, s[6:7]
	s_waitcnt vmcnt(1)
	v_lshlrev_b32_e32 v156, 16, v160
	v_and_b32_e32 v157, 0xffff0000, v160
	v_lshlrev_b32_e32 v148, 16, v161
	v_and_b32_e32 v149, 0xffff0000, v161
	v_pk_mul_f32 v[126:127], v[126:127], v[148:149]
	v_lshlrev_b32_e32 v148, 16, v162
	v_and_b32_e32 v149, 0xffff0000, v162
	v_pk_mul_f32 v[148:149], v[120:121], v[148:149]
	v_lshlrev_b32_e32 v120, 16, v163
	v_and_b32_e32 v121, 0xffff0000, v163
	v_pk_mul_f32 v[124:125], v[124:125], v[156:157]
	v_pk_mul_f32 v[150:151], v[122:123], v[120:121]
	v_lshl_add_u64 v[120:121], s[12:13], 0, v[152:153]
	v_lshl_add_u64 v[152:153], v[120:121], 0, v[138:139]
	v_cvt_pk_bf16_f32 v120, v124, v125
	v_cvt_pk_bf16_f32 v121, v126, v127
	v_cvt_pk_bf16_f32 v122, v148, v149
	v_cvt_pk_bf16_f32 v123, v150, v151
	global_store_dwordx4 v[152:153], v[120:123], off
	s_waitcnt vmcnt(0)
	v_lshlrev_b32_e32 v124, 16, v164
	v_and_b32_e32 v125, 0xffff0000, v164
	v_lshlrev_b32_e32 v120, 16, v165
	v_and_b32_e32 v121, 0xffff0000, v165
	v_pk_mul_f32 v[118:119], v[118:119], v[120:121]
	v_lshlrev_b32_e32 v120, 16, v166
	v_and_b32_e32 v121, 0xffff0000, v166
	v_pk_mul_f32 v[120:121], v[112:113], v[120:121]
	v_lshlrev_b32_e32 v112, 16, v167
	v_and_b32_e32 v113, 0xffff0000, v167
	v_pk_mul_f32 v[116:117], v[116:117], v[124:125]
	v_pk_mul_f32 v[122:123], v[114:115], v[112:113]
	v_cvt_pk_bf16_f32 v112, v116, v117
	v_cvt_pk_bf16_f32 v113, v118, v119
	v_cvt_pk_bf16_f32 v114, v120, v121
	v_cvt_pk_bf16_f32 v115, v122, v123
	global_store_dwordx4 v[152:153], v[112:115], off offset:256
	s_nop 1
	v_or_b32_e32 v112, 16, v140
	v_ashrrev_i32_e32 v113, 31, v112
	v_lshlrev_b64 v[114:115], 12, v[112:113]
	v_lshlrev_b64 v[116:117], 11, v[112:113]
	v_lshl_add_u64 v[112:113], s[10:11], 0, v[114:115]
	v_lshl_add_u64 v[118:119], v[112:113], 0, v[138:139]
	global_load_dwordx4 v[168:171], v[118:119], off
	global_load_dwordx4 v[172:175], v[118:119], off offset:256
	s_waitcnt vmcnt(1)
	v_lshlrev_b32_e32 v120, 16, v168
	v_and_b32_e32 v121, 0xffff0000, v168
	v_lshlrev_b32_e32 v112, 16, v169
	v_and_b32_e32 v113, 0xffff0000, v169
	v_pk_mul_f32 v[110:111], v[110:111], v[112:113]
	v_lshlrev_b32_e32 v112, 16, v170
	v_and_b32_e32 v113, 0xffff0000, v170
	v_pk_mul_f32 v[112:113], v[104:105], v[112:113]
	v_lshlrev_b32_e32 v104, 16, v171
	v_and_b32_e32 v105, 0xffff0000, v171
	v_pk_mul_f32 v[108:109], v[108:109], v[120:121]
	v_pk_mul_f32 v[114:115], v[106:107], v[104:105]
	v_lshl_add_u64 v[104:105], s[12:13], 0, v[116:117]
	v_lshl_add_u64 v[116:117], v[104:105], 0, v[138:139]
	v_cvt_pk_bf16_f32 v104, v108, v109
	v_cvt_pk_bf16_f32 v105, v110, v111
	v_cvt_pk_bf16_f32 v106, v112, v113
	v_cvt_pk_bf16_f32 v107, v114, v115
	global_store_dwordx4 v[116:117], v[104:107], off
	s_waitcnt vmcnt(0)
	v_lshlrev_b32_e32 v108, 16, v172
	v_and_b32_e32 v109, 0xffff0000, v172
	v_lshlrev_b32_e32 v104, 16, v173
	v_and_b32_e32 v105, 0xffff0000, v173
	v_pk_mul_f32 v[102:103], v[102:103], v[104:105]
	v_lshlrev_b32_e32 v104, 16, v174
	v_and_b32_e32 v105, 0xffff0000, v174
	v_pk_mul_f32 v[104:105], v[96:97], v[104:105]
	v_lshlrev_b32_e32 v96, 16, v175
	v_and_b32_e32 v97, 0xffff0000, v175
	v_pk_mul_f32 v[100:101], v[100:101], v[108:109]
	v_pk_mul_f32 v[106:107], v[98:99], v[96:97]
	v_cvt_pk_bf16_f32 v96, v100, v101
	v_cvt_pk_bf16_f32 v97, v102, v103
	v_cvt_pk_bf16_f32 v98, v104, v105
	v_cvt_pk_bf16_f32 v99, v106, v107
	global_store_dwordx4 v[116:117], v[96:99], off offset:256
	s_nop 1
	v_or_b32_e32 v96, 32, v140
	v_ashrrev_i32_e32 v97, 31, v96
	v_lshlrev_b64 v[98:99], 12, v[96:97]
	v_lshlrev_b64 v[100:101], 11, v[96:97]
	v_lshl_add_u64 v[96:97], s[10:11], 0, v[98:99]
	v_lshl_add_u64 v[102:103], v[96:97], 0, v[138:139]
	global_load_dwordx4 v[176:179], v[102:103], off
	global_load_dwordx4 v[180:183], v[102:103], off offset:256
	s_waitcnt vmcnt(1)
	v_lshlrev_b32_e32 v104, 16, v176
	v_and_b32_e32 v105, 0xffff0000, v176
	v_lshlrev_b32_e32 v96, 16, v177
	v_and_b32_e32 v97, 0xffff0000, v177
	v_pk_mul_f32 v[94:95], v[94:95], v[96:97]
	v_lshlrev_b32_e32 v96, 16, v178
	v_and_b32_e32 v97, 0xffff0000, v178
	v_pk_mul_f32 v[96:97], v[88:89], v[96:97]
	v_lshlrev_b32_e32 v88, 16, v179
	v_and_b32_e32 v89, 0xffff0000, v179
	v_pk_mul_f32 v[92:93], v[92:93], v[104:105]
	v_pk_mul_f32 v[98:99], v[90:91], v[88:89]
	v_lshl_add_u64 v[88:89], s[12:13], 0, v[100:101]
	v_lshl_add_u64 v[100:101], v[88:89], 0, v[138:139]
	v_cvt_pk_bf16_f32 v88, v92, v93
	v_cvt_pk_bf16_f32 v89, v94, v95
	v_cvt_pk_bf16_f32 v90, v96, v97
	v_cvt_pk_bf16_f32 v91, v98, v99
	global_store_dwordx4 v[100:101], v[88:91], off
	s_waitcnt vmcnt(0)
	v_lshlrev_b32_e32 v92, 16, v180
	v_and_b32_e32 v93, 0xffff0000, v180
	v_lshlrev_b32_e32 v88, 16, v181
	v_and_b32_e32 v89, 0xffff0000, v181
	v_pk_mul_f32 v[86:87], v[86:87], v[88:89]
	v_lshlrev_b32_e32 v88, 16, v182
	v_and_b32_e32 v89, 0xffff0000, v182
	v_pk_mul_f32 v[88:89], v[80:81], v[88:89]
	v_lshlrev_b32_e32 v80, 16, v183
	v_and_b32_e32 v81, 0xffff0000, v183
	v_pk_mul_f32 v[84:85], v[84:85], v[92:93]
	v_pk_mul_f32 v[90:91], v[82:83], v[80:81]
	v_cvt_pk_bf16_f32 v80, v84, v85
	v_cvt_pk_bf16_f32 v81, v86, v87
	v_cvt_pk_bf16_f32 v82, v88, v89
	v_cvt_pk_bf16_f32 v83, v90, v91
	global_store_dwordx4 v[100:101], v[80:83], off offset:256
	s_nop 1
	v_or_b32_e32 v80, 48, v140
	v_ashrrev_i32_e32 v81, 31, v80
	v_lshlrev_b64 v[82:83], 12, v[80:81]
	v_lshlrev_b64 v[84:85], 11, v[80:81]
	v_lshl_add_u64 v[80:81], s[10:11], 0, v[82:83]
	v_lshl_add_u64 v[86:87], v[80:81], 0, v[138:139]
	global_load_dwordx4 v[184:187], v[86:87], off
	global_load_dwordx4 v[188:191], v[86:87], off offset:256
	s_waitcnt vmcnt(1)
	v_lshlrev_b32_e32 v88, 16, v184
	v_and_b32_e32 v89, 0xffff0000, v184
	v_lshlrev_b32_e32 v80, 16, v185
	v_and_b32_e32 v81, 0xffff0000, v185
	v_pk_mul_f32 v[78:79], v[78:79], v[80:81]
	v_lshlrev_b32_e32 v80, 16, v186
	v_and_b32_e32 v81, 0xffff0000, v186
	v_pk_mul_f32 v[80:81], v[72:73], v[80:81]
	v_lshlrev_b32_e32 v72, 16, v187
	v_and_b32_e32 v73, 0xffff0000, v187
	v_pk_mul_f32 v[76:77], v[76:77], v[88:89]
	v_pk_mul_f32 v[82:83], v[74:75], v[72:73]
	v_lshl_add_u64 v[72:73], s[12:13], 0, v[84:85]
	v_lshl_add_u64 v[84:85], v[72:73], 0, v[138:139]
	v_cvt_pk_bf16_f32 v72, v76, v77
	v_cvt_pk_bf16_f32 v73, v78, v79
	v_cvt_pk_bf16_f32 v74, v80, v81
	v_cvt_pk_bf16_f32 v75, v82, v83
	global_store_dwordx4 v[84:85], v[72:75], off
	s_waitcnt vmcnt(0)
	v_lshlrev_b32_e32 v76, 16, v188
	v_and_b32_e32 v77, 0xffff0000, v188
	v_lshlrev_b32_e32 v72, 16, v189
	v_and_b32_e32 v73, 0xffff0000, v189
	v_pk_mul_f32 v[70:71], v[70:71], v[72:73]
	v_lshlrev_b32_e32 v72, 16, v190
	v_and_b32_e32 v73, 0xffff0000, v190
	v_pk_mul_f32 v[72:73], v[64:65], v[72:73]
	v_lshlrev_b32_e32 v64, 16, v191
	v_and_b32_e32 v65, 0xffff0000, v191
	v_pk_mul_f32 v[68:69], v[68:69], v[76:77]
	v_pk_mul_f32 v[74:75], v[66:67], v[64:65]
	v_cvt_pk_bf16_f32 v64, v68, v69
	v_cvt_pk_bf16_f32 v65, v70, v71
	v_cvt_pk_bf16_f32 v66, v72, v73
	v_cvt_pk_bf16_f32 v67, v74, v75
	global_store_dwordx4 v[84:85], v[64:67], off offset:256
	s_nop 1
	v_add_u32_e32 v64, 0x80, v140
	v_ashrrev_i32_e32 v65, 31, v64
	v_lshlrev_b64 v[66:67], 12, v[64:65]
	v_lshlrev_b64 v[68:69], 11, v[64:65]
	v_lshl_add_u64 v[64:65], s[10:11], 0, v[66:67]
	v_lshl_add_u64 v[70:71], v[64:65], 0, v[138:139]
	global_load_dwordx4 v[192:195], v[70:71], off
	global_load_dwordx4 v[196:199], v[70:71], off offset:256
	s_waitcnt vmcnt(1)
	v_lshlrev_b32_e32 v72, 16, v192
	v_and_b32_e32 v73, 0xffff0000, v192
	v_lshlrev_b32_e32 v64, 16, v193
	v_and_b32_e32 v65, 0xffff0000, v193
	v_pk_mul_f32 v[62:63], v[62:63], v[64:65]
	v_lshlrev_b32_e32 v64, 16, v194
	v_and_b32_e32 v65, 0xffff0000, v194
	v_pk_mul_f32 v[64:65], v[56:57], v[64:65]
	v_lshlrev_b32_e32 v56, 16, v195
	v_and_b32_e32 v57, 0xffff0000, v195
	v_pk_mul_f32 v[60:61], v[60:61], v[72:73]
	v_pk_mul_f32 v[66:67], v[58:59], v[56:57]
	v_lshl_add_u64 v[56:57], s[12:13], 0, v[68:69]
	v_lshl_add_u64 v[68:69], v[56:57], 0, v[138:139]
	v_cvt_pk_bf16_f32 v56, v60, v61
	v_cvt_pk_bf16_f32 v57, v62, v63
	v_cvt_pk_bf16_f32 v58, v64, v65
	v_cvt_pk_bf16_f32 v59, v66, v67
	global_store_dwordx4 v[68:69], v[56:59], off
	s_waitcnt vmcnt(0)
	v_lshlrev_b32_e32 v60, 16, v196
	v_and_b32_e32 v61, 0xffff0000, v196
	v_lshlrev_b32_e32 v56, 16, v197
	v_and_b32_e32 v57, 0xffff0000, v197
	v_pk_mul_f32 v[54:55], v[54:55], v[56:57]
	v_lshlrev_b32_e32 v56, 16, v198
	v_and_b32_e32 v57, 0xffff0000, v198
	v_pk_mul_f32 v[56:57], v[48:49], v[56:57]
	v_lshlrev_b32_e32 v48, 16, v199
	v_and_b32_e32 v49, 0xffff0000, v199
	v_pk_mul_f32 v[52:53], v[52:53], v[60:61]
	v_pk_mul_f32 v[58:59], v[50:51], v[48:49]
	v_cvt_pk_bf16_f32 v48, v52, v53
	v_cvt_pk_bf16_f32 v49, v54, v55
	v_cvt_pk_bf16_f32 v50, v56, v57
	v_cvt_pk_bf16_f32 v51, v58, v59
	global_store_dwordx4 v[68:69], v[48:51], off offset:256
	s_nop 1
	v_add_u32_e32 v48, 0x90, v140
	v_ashrrev_i32_e32 v49, 31, v48
	v_lshlrev_b64 v[50:51], 12, v[48:49]
	v_lshlrev_b64 v[52:53], 11, v[48:49]
	v_lshl_add_u64 v[48:49], s[10:11], 0, v[50:51]
	v_lshl_add_u64 v[54:55], v[48:49], 0, v[138:139]
	global_load_dwordx4 v[200:203], v[54:55], off
	global_load_dwordx4 v[204:207], v[54:55], off offset:256
	s_waitcnt vmcnt(1)
	v_lshlrev_b32_e32 v56, 16, v200
	v_and_b32_e32 v57, 0xffff0000, v200
	v_lshlrev_b32_e32 v48, 16, v201
	v_and_b32_e32 v49, 0xffff0000, v201
	v_pk_mul_f32 v[46:47], v[46:47], v[48:49]
	v_lshlrev_b32_e32 v48, 16, v202
	v_and_b32_e32 v49, 0xffff0000, v202
	v_pk_mul_f32 v[48:49], v[40:41], v[48:49]
	v_lshlrev_b32_e32 v40, 16, v203
	v_and_b32_e32 v41, 0xffff0000, v203
	v_pk_mul_f32 v[44:45], v[44:45], v[56:57]
	v_pk_mul_f32 v[50:51], v[42:43], v[40:41]
	v_lshl_add_u64 v[40:41], s[12:13], 0, v[52:53]
	v_lshl_add_u64 v[52:53], v[40:41], 0, v[138:139]
	v_cvt_pk_bf16_f32 v40, v44, v45
	v_cvt_pk_bf16_f32 v41, v46, v47
	v_cvt_pk_bf16_f32 v42, v48, v49
	v_cvt_pk_bf16_f32 v43, v50, v51
	global_store_dwordx4 v[52:53], v[40:43], off
	s_waitcnt vmcnt(0)
	v_lshlrev_b32_e32 v44, 16, v204
	v_and_b32_e32 v45, 0xffff0000, v204
	v_lshlrev_b32_e32 v40, 16, v205
	v_and_b32_e32 v41, 0xffff0000, v205
	v_pk_mul_f32 v[38:39], v[38:39], v[40:41]
	v_lshlrev_b32_e32 v40, 16, v206
	v_and_b32_e32 v41, 0xffff0000, v206
	v_pk_mul_f32 v[40:41], v[32:33], v[40:41]
	v_lshlrev_b32_e32 v32, 16, v207
	v_and_b32_e32 v33, 0xffff0000, v207
	v_pk_mul_f32 v[36:37], v[36:37], v[44:45]
	v_pk_mul_f32 v[42:43], v[34:35], v[32:33]
	v_cvt_pk_bf16_f32 v32, v36, v37
	v_cvt_pk_bf16_f32 v33, v38, v39
	v_cvt_pk_bf16_f32 v34, v40, v41
	v_cvt_pk_bf16_f32 v35, v42, v43
	global_store_dwordx4 v[52:53], v[32:35], off offset:256
	s_nop 1
	v_add_u32_e32 v32, 0xa0, v140
	v_ashrrev_i32_e32 v33, 31, v32
	v_lshlrev_b64 v[34:35], 12, v[32:33]
	v_lshlrev_b64 v[36:37], 11, v[32:33]
	v_lshl_add_u64 v[32:33], s[10:11], 0, v[34:35]
	v_lshl_add_u64 v[38:39], v[32:33], 0, v[138:139]
	global_load_dwordx4 v[160:163], v[38:39], off
	global_load_dwordx4 v[164:167], v[38:39], off offset:256
	s_waitcnt vmcnt(1)
	v_lshlrev_b32_e32 v40, 16, v160
	v_and_b32_e32 v41, 0xffff0000, v160
	v_lshlrev_b32_e32 v32, 16, v161
	v_and_b32_e32 v33, 0xffff0000, v161
	v_pk_mul_f32 v[30:31], v[30:31], v[32:33]
	v_lshlrev_b32_e32 v32, 16, v162
	v_and_b32_e32 v33, 0xffff0000, v162
	v_pk_mul_f32 v[32:33], v[24:25], v[32:33]
	v_lshlrev_b32_e32 v24, 16, v163
	v_and_b32_e32 v25, 0xffff0000, v163
	v_pk_mul_f32 v[28:29], v[28:29], v[40:41]
	v_pk_mul_f32 v[34:35], v[26:27], v[24:25]
	v_lshl_add_u64 v[24:25], s[12:13], 0, v[36:37]
	v_lshl_add_u64 v[36:37], v[24:25], 0, v[138:139]
	v_cvt_pk_bf16_f32 v24, v28, v29
	v_cvt_pk_bf16_f32 v25, v30, v31
	v_cvt_pk_bf16_f32 v26, v32, v33
	v_cvt_pk_bf16_f32 v27, v34, v35
	global_store_dwordx4 v[36:37], v[24:27], off
	s_waitcnt vmcnt(0)
	v_lshlrev_b32_e32 v28, 16, v164
	v_and_b32_e32 v29, 0xffff0000, v164
	v_lshlrev_b32_e32 v24, 16, v165
	v_and_b32_e32 v25, 0xffff0000, v165
	v_pk_mul_f32 v[22:23], v[22:23], v[24:25]
	v_lshlrev_b32_e32 v24, 16, v166
	v_and_b32_e32 v25, 0xffff0000, v166
	v_pk_mul_f32 v[24:25], v[16:17], v[24:25]
	v_lshlrev_b32_e32 v16, 16, v167
	v_and_b32_e32 v17, 0xffff0000, v167
	v_pk_mul_f32 v[20:21], v[20:21], v[28:29]
	v_pk_mul_f32 v[26:27], v[18:19], v[16:17]
	v_cvt_pk_bf16_f32 v16, v20, v21
	v_cvt_pk_bf16_f32 v17, v22, v23
	v_cvt_pk_bf16_f32 v18, v24, v25
	v_cvt_pk_bf16_f32 v19, v26, v27
	global_store_dwordx4 v[36:37], v[16:19], off offset:256
	s_nop 1
	v_add_u32_e32 v16, 0xb0, v140
	v_ashrrev_i32_e32 v17, 31, v16
	v_lshlrev_b64 v[18:19], 12, v[16:17]
	v_lshlrev_b64 v[20:21], 11, v[16:17]
	v_lshl_add_u64 v[16:17], s[10:11], 0, v[18:19]
	v_lshl_add_u64 v[22:23], v[16:17], 0, v[138:139]
	global_load_dwordx4 v[168:171], v[22:23], off
	global_load_dwordx4 v[172:175], v[22:23], off offset:256
	s_waitcnt vmcnt(1)
	v_lshlrev_b32_e32 v24, 16, v168
	v_and_b32_e32 v25, 0xffff0000, v168
	v_lshlrev_b32_e32 v16, 16, v169
	v_and_b32_e32 v17, 0xffff0000, v169
	v_pk_mul_f32 v[14:15], v[14:15], v[16:17]
	v_lshlrev_b32_e32 v16, 16, v170
	v_and_b32_e32 v17, 0xffff0000, v170
	v_pk_mul_f32 v[16:17], v[8:9], v[16:17]
	v_lshlrev_b32_e32 v8, 16, v171
	v_and_b32_e32 v9, 0xffff0000, v171
	v_pk_mul_f32 v[12:13], v[12:13], v[24:25]
	v_pk_mul_f32 v[18:19], v[10:11], v[8:9]
	v_lshl_add_u64 v[8:9], s[12:13], 0, v[20:21]
	v_lshl_add_u64 v[20:21], v[8:9], 0, v[138:139]
	v_cvt_pk_bf16_f32 v8, v12, v13
	v_cvt_pk_bf16_f32 v9, v14, v15
	v_cvt_pk_bf16_f32 v10, v16, v17
	v_cvt_pk_bf16_f32 v11, v18, v19
	global_store_dwordx4 v[20:21], v[8:11], off
	s_waitcnt vmcnt(0)
	v_lshlrev_b32_e32 v12, 16, v172
	v_and_b32_e32 v13, 0xffff0000, v172
	v_lshlrev_b32_e32 v8, 16, v173
	v_and_b32_e32 v9, 0xffff0000, v173
	v_pk_mul_f32 v[6:7], v[6:7], v[8:9]
	v_lshlrev_b32_e32 v8, 16, v174
	v_and_b32_e32 v9, 0xffff0000, v174
	v_pk_mul_f32 v[8:9], v[0:1], v[8:9]
	v_lshlrev_b32_e32 v0, 16, v175
	v_and_b32_e32 v1, 0xffff0000, v175
	v_pk_mul_f32 v[4:5], v[4:5], v[12:13]
	v_pk_mul_f32 v[10:11], v[2:3], v[0:1]
	v_cvt_pk_bf16_f32 v0, v4, v5
	v_cvt_pk_bf16_f32 v1, v6, v7
	v_cvt_pk_bf16_f32 v2, v8, v9
	v_cvt_pk_bf16_f32 v3, v10, v11
	global_store_dwordx4 v[20:21], v[0:3], off offset:256
	s_cbranch_vccnz .LBB0_1301
	s_andn2_b64 vcc, exec, s[14:15]
	s_cbranch_vccnz .LBB0_1300
	s_barrier
	s_branch .LBB0_1300

.LBB0_1332:
	v_lshl_add_u32 v140, s5, 8, v143
	v_lshl_or_b32 v138, s4, 8, v145
	v_ashrrev_i32_e32 v141, 31, v140
	v_lshlrev_b64 v[148:149], 12, v[140:141]
	v_lshlrev_b64 v[152:153], 11, v[140:141]
	v_ashrrev_i32_e32 v139, 31, v138
	v_lshl_add_u64 v[148:149], s[10:11], 0, v[148:149]
	v_lshlrev_b64 v[138:139], 1, v[138:139]
	v_lshl_add_u64 v[152:153], s[12:13], 0, v[152:153]
	v_lshl_add_u64 v[156:157], v[148:149], 0, v[138:139]
	v_lshl_add_u64 v[158:159], v[152:153], 0, v[138:139]
	global_load_dwordx4 v[164:167], v[156:157], off offset:2048
	global_load_dwordx4 v[168:171], v[158:159], off
	global_load_dwordx4 v[172:175], v[156:157], off offset:2304
	global_load_dwordx4 v[176:179], v[158:159], off offset:256
	s_mov_b64 s[0:1], -1
	s_andn2_b64 vcc, exec, s[6:7]
	s_waitcnt vmcnt(2)
	v_lshlrev_b32_e32 v160, 16, v164
	v_and_b32_e32 v161, 0xffff0000, v164
	v_lshlrev_b32_e32 v162, 16, v168
	v_and_b32_e32 v163, 0xffff0000, v168
	v_lshlrev_b32_e32 v148, 16, v165
	v_and_b32_e32 v149, 0xffff0000, v165
	v_lshlrev_b32_e32 v152, 16, v169
	v_and_b32_e32 v153, 0xffff0000, v169
	v_pk_fma_f32 v[126:127], v[126:127], v[148:149], v[152:153]
	v_lshlrev_b32_e32 v148, 16, v166
	v_and_b32_e32 v149, 0xffff0000, v166
	v_lshlrev_b32_e32 v152, 16, v170
	v_and_b32_e32 v153, 0xffff0000, v170
	v_pk_fma_f32 v[148:149], v[120:121], v[148:149], v[152:153]
	v_lshlrev_b32_e32 v120, 16, v167
	v_and_b32_e32 v121, 0xffff0000, v167
	v_lshlrev_b32_e32 v150, 16, v171
	v_and_b32_e32 v151, 0xffff0000, v171
	v_pk_fma_f32 v[124:125], v[124:125], v[160:161], v[162:163]
	v_pk_fma_f32 v[150:151], v[122:123], v[120:121], v[150:151]
	v_cvt_pk_bf16_f32 v120, v124, v125
	v_cvt_pk_bf16_f32 v121, v126, v127
	v_cvt_pk_bf16_f32 v122, v148, v149
	v_cvt_pk_bf16_f32 v123, v150, v151
	global_store_dwordx4 v[158:159], v[120:123], off
	s_nop 0
	s_waitcnt vmcnt(0)
	v_lshlrev_b32_e32 v148, 16, v172
	v_and_b32_e32 v149, 0xffff0000, v172
	s_waitcnt vmcnt(0)
	v_lshlrev_b32_e32 v150, 16, v176
	v_and_b32_e32 v151, 0xffff0000, v176
	v_lshlrev_b32_e32 v120, 16, v173
	v_and_b32_e32 v121, 0xffff0000, v173
	v_lshlrev_b32_e32 v124, 16, v177
	v_and_b32_e32 v125, 0xffff0000, v177
	v_pk_fma_f32 v[118:119], v[118:119], v[120:121], v[124:125]
	v_lshlrev_b32_e32 v120, 16, v174
	v_and_b32_e32 v121, 0xffff0000, v174
	v_lshlrev_b32_e32 v124, 16, v178
	v_and_b32_e32 v125, 0xffff0000, v178
	v_pk_fma_f32 v[120:121], v[112:113], v[120:121], v[124:125]
	v_lshlrev_b32_e32 v112, 16, v175
	v_and_b32_e32 v113, 0xffff0000, v175
	v_lshlrev_b32_e32 v122, 16, v179
	v_and_b32_e32 v123, 0xffff0000, v179
	v_pk_fma_f32 v[116:117], v[116:117], v[148:149], v[150:151]
	v_pk_fma_f32 v[122:123], v[114:115], v[112:113], v[122:123]
	v_cvt_pk_bf16_f32 v112, v116, v117
	v_cvt_pk_bf16_f32 v113, v118, v119
	v_cvt_pk_bf16_f32 v114, v120, v121
	v_cvt_pk_bf16_f32 v115, v122, v123
	global_store_dwordx4 v[158:159], v[112:115], off offset:256
	s_nop 1
	v_or_b32_e32 v112, 16, v140
	v_ashrrev_i32_e32 v113, 31, v112
	v_lshlrev_b64 v[114:115], 12, v[112:113]
	v_lshlrev_b64 v[116:117], 11, v[112:113]
	v_lshl_add_u64 v[112:113], s[10:11], 0, v[114:115]
	v_lshl_add_u64 v[116:117], s[12:13], 0, v[116:117]
	v_lshl_add_u64 v[120:121], v[112:113], 0, v[138:139]
	global_load_dwordx4 v[180:183], v[120:121], off offset:2048
	v_lshl_add_u64 v[122:123], v[116:117], 0, v[138:139]
	global_load_dwordx4 v[184:187], v[122:123], off
	global_load_dwordx4 v[188:191], v[120:121], off offset:2304
	global_load_dwordx4 v[192:195], v[122:123], off offset:256
	s_waitcnt vmcnt(3)
	v_lshlrev_b32_e32 v124, 16, v180
	v_and_b32_e32 v125, 0xffff0000, v180
	s_waitcnt vmcnt(2)
	v_lshlrev_b32_e32 v126, 16, v184
	v_and_b32_e32 v127, 0xffff0000, v184
	v_lshlrev_b32_e32 v112, 16, v181
	v_and_b32_e32 v113, 0xffff0000, v181
	v_lshlrev_b32_e32 v116, 16, v185
	v_and_b32_e32 v117, 0xffff0000, v185
	v_pk_fma_f32 v[110:111], v[110:111], v[112:113], v[116:117]
	v_lshlrev_b32_e32 v112, 16, v182
	v_and_b32_e32 v113, 0xffff0000, v182
	v_lshlrev_b32_e32 v116, 16, v186
	v_and_b32_e32 v117, 0xffff0000, v186
	v_pk_fma_f32 v[112:113], v[104:105], v[112:113], v[116:117]
	v_lshlrev_b32_e32 v104, 16, v183
	v_and_b32_e32 v105, 0xffff0000, v183
	v_lshlrev_b32_e32 v114, 16, v187
	v_and_b32_e32 v115, 0xffff0000, v187
	v_pk_fma_f32 v[108:109], v[108:109], v[124:125], v[126:127]
	v_pk_fma_f32 v[114:115], v[106:107], v[104:105], v[114:115]
	v_cvt_pk_bf16_f32 v104, v108, v109
	v_cvt_pk_bf16_f32 v105, v110, v111
	v_cvt_pk_bf16_f32 v106, v112, v113
	v_cvt_pk_bf16_f32 v107, v114, v115
	global_store_dwordx4 v[122:123], v[104:107], off
	s_nop 0
	s_waitcnt vmcnt(0)
	v_lshlrev_b32_e32 v112, 16, v188
	v_and_b32_e32 v113, 0xffff0000, v188
	s_waitcnt vmcnt(0)
	v_lshlrev_b32_e32 v114, 16, v192
	v_and_b32_e32 v115, 0xffff0000, v192
	v_lshlrev_b32_e32 v104, 16, v189
	v_and_b32_e32 v105, 0xffff0000, v189
	v_lshlrev_b32_e32 v108, 16, v193
	v_and_b32_e32 v109, 0xffff0000, v193
	v_pk_fma_f32 v[102:103], v[102:103], v[104:105], v[108:109]
	v_lshlrev_b32_e32 v104, 16, v190
	v_and_b32_e32 v105, 0xffff0000, v190
	v_lshlrev_b32_e32 v108, 16, v194
	v_and_b32_e32 v109, 0xffff0000, v194
	v_pk_fma_f32 v[104:105], v[96:97], v[104:105], v[108:109]
	v_lshlrev_b32_e32 v96, 16, v191
	v_and_b32_e32 v97, 0xffff0000, v191
	v_lshlrev_b32_e32 v106, 16, v195
	v_and_b32_e32 v107, 0xffff0000, v195
	v_pk_fma_f32 v[100:101], v[100:101], v[112:113], v[114:115]
	v_pk_fma_f32 v[106:107], v[98:99], v[96:97], v[106:107]
	v_cvt_pk_bf16_f32 v96, v100, v101
	v_cvt_pk_bf16_f32 v97, v102, v103
	v_cvt_pk_bf16_f32 v98, v104, v105
	v_cvt_pk_bf16_f32 v99, v106, v107
	global_store_dwordx4 v[122:123], v[96:99], off offset:256
	s_nop 1
	v_or_b32_e32 v96, 32, v140
	v_ashrrev_i32_e32 v97, 31, v96
	v_lshlrev_b64 v[98:99], 12, v[96:97]
	v_lshlrev_b64 v[100:101], 11, v[96:97]
	v_lshl_add_u64 v[96:97], s[10:11], 0, v[98:99]
	v_lshl_add_u64 v[100:101], s[12:13], 0, v[100:101]
	v_lshl_add_u64 v[104:105], v[96:97], 0, v[138:139]
	global_load_dwordx4 v[196:199], v[104:105], off offset:2048
	v_lshl_add_u64 v[106:107], v[100:101], 0, v[138:139]
	global_load_dwordx4 v[200:203], v[106:107], off
	global_load_dwordx4 v[204:207], v[104:105], off offset:2304
	global_load_dwordx4 v[164:167], v[106:107], off offset:256
	s_waitcnt vmcnt(3)
	v_lshlrev_b32_e32 v108, 16, v196
	v_and_b32_e32 v109, 0xffff0000, v196
	s_waitcnt vmcnt(2)
	v_lshlrev_b32_e32 v110, 16, v200
	v_and_b32_e32 v111, 0xffff0000, v200
	v_lshlrev_b32_e32 v96, 16, v197
	v_and_b32_e32 v97, 0xffff0000, v197
	v_lshlrev_b32_e32 v100, 16, v201
	v_and_b32_e32 v101, 0xffff0000, v201
	v_pk_fma_f32 v[94:95], v[94:95], v[96:97], v[100:101]
	v_lshlrev_b32_e32 v96, 16, v198
	v_and_b32_e32 v97, 0xffff0000, v198
	v_lshlrev_b32_e32 v100, 16, v202
	v_and_b32_e32 v101, 0xffff0000, v202
	v_pk_fma_f32 v[96:97], v[88:89], v[96:97], v[100:101]
	v_lshlrev_b32_e32 v88, 16, v199
	v_and_b32_e32 v89, 0xffff0000, v199
	v_lshlrev_b32_e32 v98, 16, v203
	v_and_b32_e32 v99, 0xffff0000, v203
	v_pk_fma_f32 v[92:93], v[92:93], v[108:109], v[110:111]
	v_pk_fma_f32 v[98:99], v[90:91], v[88:89], v[98:99]
	v_cvt_pk_bf16_f32 v88, v92, v93
	v_cvt_pk_bf16_f32 v89, v94, v95
	v_cvt_pk_bf16_f32 v90, v96, v97
	v_cvt_pk_bf16_f32 v91, v98, v99
	global_store_dwordx4 v[106:107], v[88:91], off
	s_nop 0
	s_waitcnt vmcnt(0)
	v_lshlrev_b32_e32 v96, 16, v204
	v_and_b32_e32 v97, 0xffff0000, v204
	s_waitcnt vmcnt(0)
	v_lshlrev_b32_e32 v98, 16, v164
	v_and_b32_e32 v99, 0xffff0000, v164
	v_lshlrev_b32_e32 v88, 16, v205
	v_and_b32_e32 v89, 0xffff0000, v205
	v_lshlrev_b32_e32 v92, 16, v165
	v_and_b32_e32 v93, 0xffff0000, v165
	v_pk_fma_f32 v[86:87], v[86:87], v[88:89], v[92:93]
	v_lshlrev_b32_e32 v88, 16, v206
	v_and_b32_e32 v89, 0xffff0000, v206
	v_lshlrev_b32_e32 v92, 16, v166
	v_and_b32_e32 v93, 0xffff0000, v166
	v_pk_fma_f32 v[88:89], v[80:81], v[88:89], v[92:93]
	v_lshlrev_b32_e32 v80, 16, v207
	v_and_b32_e32 v81, 0xffff0000, v207
	v_lshlrev_b32_e32 v90, 16, v167
	v_and_b32_e32 v91, 0xffff0000, v167
	v_pk_fma_f32 v[84:85], v[84:85], v[96:97], v[98:99]
	v_pk_fma_f32 v[90:91], v[82:83], v[80:81], v[90:91]
	v_cvt_pk_bf16_f32 v80, v84, v85
	v_cvt_pk_bf16_f32 v81, v86, v87
	v_cvt_pk_bf16_f32 v82, v88, v89
	v_cvt_pk_bf16_f32 v83, v90, v91
	global_store_dwordx4 v[106:107], v[80:83], off offset:256
	s_nop 1
	v_or_b32_e32 v80, 48, v140
	v_ashrrev_i32_e32 v81, 31, v80
	v_lshlrev_b64 v[82:83], 12, v[80:81]
	v_lshlrev_b64 v[84:85], 11, v[80:81]
	v_lshl_add_u64 v[80:81], s[10:11], 0, v[82:83]
	v_lshl_add_u64 v[84:85], s[12:13], 0, v[84:85]
	v_lshl_add_u64 v[88:89], v[80:81], 0, v[138:139]
	global_load_dwordx4 v[168:171], v[88:89], off offset:2048
	v_lshl_add_u64 v[90:91], v[84:85], 0, v[138:139]
	global_load_dwordx4 v[172:175], v[90:91], off
	global_load_dwordx4 v[176:179], v[88:89], off offset:2304
	global_load_dwordx4 v[180:183], v[90:91], off offset:256
	s_waitcnt vmcnt(3)
	v_lshlrev_b32_e32 v92, 16, v168
	v_and_b32_e32 v93, 0xffff0000, v168
	s_waitcnt vmcnt(2)
	v_lshlrev_b32_e32 v94, 16, v172
	v_and_b32_e32 v95, 0xffff0000, v172
	v_lshlrev_b32_e32 v80, 16, v169
	v_and_b32_e32 v81, 0xffff0000, v169
	v_lshlrev_b32_e32 v84, 16, v173
	v_and_b32_e32 v85, 0xffff0000, v173
	v_pk_fma_f32 v[78:79], v[78:79], v[80:81], v[84:85]
	v_lshlrev_b32_e32 v80, 16, v170
	v_and_b32_e32 v81, 0xffff0000, v170
	v_lshlrev_b32_e32 v84, 16, v174
	v_and_b32_e32 v85, 0xffff0000, v174
	v_pk_fma_f32 v[80:81], v[72:73], v[80:81], v[84:85]
	v_lshlrev_b32_e32 v72, 16, v171
	v_and_b32_e32 v73, 0xffff0000, v171
	v_lshlrev_b32_e32 v82, 16, v175
	v_and_b32_e32 v83, 0xffff0000, v175
	v_pk_fma_f32 v[76:77], v[76:77], v[92:93], v[94:95]
	v_pk_fma_f32 v[82:83], v[74:75], v[72:73], v[82:83]
	v_cvt_pk_bf16_f32 v72, v76, v77
	v_cvt_pk_bf16_f32 v73, v78, v79
	v_cvt_pk_bf16_f32 v74, v80, v81
	v_cvt_pk_bf16_f32 v75, v82, v83
	global_store_dwordx4 v[90:91], v[72:75], off
	s_nop 0
	s_waitcnt vmcnt(0)
	v_lshlrev_b32_e32 v80, 16, v176
	v_and_b32_e32 v81, 0xffff0000, v176
	s_waitcnt vmcnt(0)
	v_lshlrev_b32_e32 v82, 16, v180
	v_and_b32_e32 v83, 0xffff0000, v180
	v_lshlrev_b32_e32 v72, 16, v177
	v_and_b32_e32 v73, 0xffff0000, v177
	v_lshlrev_b32_e32 v76, 16, v181
	v_and_b32_e32 v77, 0xffff0000, v181
	v_pk_fma_f32 v[70:71], v[70:71], v[72:73], v[76:77]
	v_lshlrev_b32_e32 v72, 16, v178
	v_and_b32_e32 v73, 0xffff0000, v178
	v_lshlrev_b32_e32 v76, 16, v182
	v_and_b32_e32 v77, 0xffff0000, v182
	v_pk_fma_f32 v[72:73], v[64:65], v[72:73], v[76:77]
	v_lshlrev_b32_e32 v64, 16, v179
	v_and_b32_e32 v65, 0xffff0000, v179
	v_lshlrev_b32_e32 v74, 16, v183
	v_and_b32_e32 v75, 0xffff0000, v183
	v_pk_fma_f32 v[68:69], v[68:69], v[80:81], v[82:83]
	v_pk_fma_f32 v[74:75], v[66:67], v[64:65], v[74:75]
	v_cvt_pk_bf16_f32 v64, v68, v69
	v_cvt_pk_bf16_f32 v65, v70, v71
	v_cvt_pk_bf16_f32 v66, v72, v73
	v_cvt_pk_bf16_f32 v67, v74, v75
	global_store_dwordx4 v[90:91], v[64:67], off offset:256
	s_nop 1
	v_add_u32_e32 v64, 0x80, v140
	v_ashrrev_i32_e32 v65, 31, v64
	v_lshlrev_b64 v[66:67], 12, v[64:65]
	v_lshlrev_b64 v[68:69], 11, v[64:65]
	v_lshl_add_u64 v[64:65], s[10:11], 0, v[66:67]
	v_lshl_add_u64 v[68:69], s[12:13], 0, v[68:69]
	v_lshl_add_u64 v[72:73], v[64:65], 0, v[138:139]
	global_load_dwordx4 v[184:187], v[72:73], off offset:2048
	v_lshl_add_u64 v[74:75], v[68:69], 0, v[138:139]
	global_load_dwordx4 v[188:191], v[74:75], off
	global_load_dwordx4 v[192:195], v[72:73], off offset:2304
	global_load_dwordx4 v[196:199], v[74:75], off offset:256
	s_waitcnt vmcnt(3)
	v_lshlrev_b32_e32 v76, 16, v184
	v_and_b32_e32 v77, 0xffff0000, v184
	s_waitcnt vmcnt(2)
	v_lshlrev_b32_e32 v78, 16, v188
	v_and_b32_e32 v79, 0xffff0000, v188
	v_lshlrev_b32_e32 v64, 16, v185
	v_and_b32_e32 v65, 0xffff0000, v185
	v_lshlrev_b32_e32 v68, 16, v189
	v_and_b32_e32 v69, 0xffff0000, v189
	v_pk_fma_f32 v[62:63], v[62:63], v[64:65], v[68:69]
	v_lshlrev_b32_e32 v64, 16, v186
	v_and_b32_e32 v65, 0xffff0000, v186
	v_lshlrev_b32_e32 v68, 16, v190
	v_and_b32_e32 v69, 0xffff0000, v190
	v_pk_fma_f32 v[64:65], v[56:57], v[64:65], v[68:69]
	v_lshlrev_b32_e32 v56, 16, v187
	v_and_b32_e32 v57, 0xffff0000, v187
	v_lshlrev_b32_e32 v66, 16, v191
	v_and_b32_e32 v67, 0xffff0000, v191
	v_pk_fma_f32 v[60:61], v[60:61], v[76:77], v[78:79]
	v_pk_fma_f32 v[66:67], v[58:59], v[56:57], v[66:67]
	v_cvt_pk_bf16_f32 v56, v60, v61
	v_cvt_pk_bf16_f32 v57, v62, v63
	v_cvt_pk_bf16_f32 v58, v64, v65
	v_cvt_pk_bf16_f32 v59, v66, v67
	global_store_dwordx4 v[74:75], v[56:59], off
	s_nop 0
	s_waitcnt vmcnt(0)
	v_lshlrev_b32_e32 v64, 16, v192
	v_and_b32_e32 v65, 0xffff0000, v192
	s_waitcnt vmcnt(0)
	v_lshlrev_b32_e32 v66, 16, v196
	v_and_b32_e32 v67, 0xffff0000, v196
	v_lshlrev_b32_e32 v56, 16, v193
	v_and_b32_e32 v57, 0xffff0000, v193
	v_lshlrev_b32_e32 v60, 16, v197
	v_and_b32_e32 v61, 0xffff0000, v197
	v_pk_fma_f32 v[54:55], v[54:55], v[56:57], v[60:61]
	v_lshlrev_b32_e32 v56, 16, v194
	v_and_b32_e32 v57, 0xffff0000, v194
	v_lshlrev_b32_e32 v60, 16, v198
	v_and_b32_e32 v61, 0xffff0000, v198
	v_pk_fma_f32 v[56:57], v[48:49], v[56:57], v[60:61]
	v_lshlrev_b32_e32 v48, 16, v195
	v_and_b32_e32 v49, 0xffff0000, v195
	v_lshlrev_b32_e32 v58, 16, v199
	v_and_b32_e32 v59, 0xffff0000, v199
	v_pk_fma_f32 v[52:53], v[52:53], v[64:65], v[66:67]
	v_pk_fma_f32 v[58:59], v[50:51], v[48:49], v[58:59]
	v_cvt_pk_bf16_f32 v48, v52, v53
	v_cvt_pk_bf16_f32 v49, v54, v55
	v_cvt_pk_bf16_f32 v50, v56, v57
	v_cvt_pk_bf16_f32 v51, v58, v59
	global_store_dwordx4 v[74:75], v[48:51], off offset:256
	s_nop 1
	v_add_u32_e32 v48, 0x90, v140
	v_ashrrev_i32_e32 v49, 31, v48
	v_lshlrev_b64 v[50:51], 12, v[48:49]
	v_lshlrev_b64 v[52:53], 11, v[48:49]
	v_lshl_add_u64 v[48:49], s[10:11], 0, v[50:51]
	v_lshl_add_u64 v[52:53], s[12:13], 0, v[52:53]
	v_lshl_add_u64 v[56:57], v[48:49], 0, v[138:139]
	global_load_dwordx4 v[200:203], v[56:57], off offset:2048
	v_lshl_add_u64 v[58:59], v[52:53], 0, v[138:139]
	global_load_dwordx4 v[204:207], v[58:59], off
	global_load_dwordx4 v[164:167], v[56:57], off offset:2304
	global_load_dwordx4 v[168:171], v[58:59], off offset:256
	s_waitcnt vmcnt(3)
	v_lshlrev_b32_e32 v60, 16, v200
	v_and_b32_e32 v61, 0xffff0000, v200
	s_waitcnt vmcnt(2)
	v_lshlrev_b32_e32 v62, 16, v204
	v_and_b32_e32 v63, 0xffff0000, v204
	v_lshlrev_b32_e32 v48, 16, v201
	v_and_b32_e32 v49, 0xffff0000, v201
	v_lshlrev_b32_e32 v52, 16, v205
	v_and_b32_e32 v53, 0xffff0000, v205
	v_pk_fma_f32 v[46:47], v[46:47], v[48:49], v[52:53]
	v_lshlrev_b32_e32 v48, 16, v202
	v_and_b32_e32 v49, 0xffff0000, v202
	v_lshlrev_b32_e32 v52, 16, v206
	v_and_b32_e32 v53, 0xffff0000, v206
	v_pk_fma_f32 v[48:49], v[40:41], v[48:49], v[52:53]
	v_lshlrev_b32_e32 v40, 16, v203
	v_and_b32_e32 v41, 0xffff0000, v203
	v_lshlrev_b32_e32 v50, 16, v207
	v_and_b32_e32 v51, 0xffff0000, v207
	v_pk_fma_f32 v[44:45], v[44:45], v[60:61], v[62:63]
	v_pk_fma_f32 v[50:51], v[42:43], v[40:41], v[50:51]
	v_cvt_pk_bf16_f32 v40, v44, v45
	v_cvt_pk_bf16_f32 v41, v46, v47
	v_cvt_pk_bf16_f32 v42, v48, v49
	v_cvt_pk_bf16_f32 v43, v50, v51
	global_store_dwordx4 v[58:59], v[40:43], off
	s_nop 0
	s_waitcnt vmcnt(0)
	v_lshlrev_b32_e32 v48, 16, v164
	v_and_b32_e32 v49, 0xffff0000, v164
	s_waitcnt vmcnt(0)
	v_lshlrev_b32_e32 v50, 16, v168
	v_and_b32_e32 v51, 0xffff0000, v168
	v_lshlrev_b32_e32 v40, 16, v165
	v_and_b32_e32 v41, 0xffff0000, v165
	v_lshlrev_b32_e32 v44, 16, v169
	v_and_b32_e32 v45, 0xffff0000, v169
	v_pk_fma_f32 v[38:39], v[38:39], v[40:41], v[44:45]
	v_lshlrev_b32_e32 v40, 16, v166
	v_and_b32_e32 v41, 0xffff0000, v166
	v_lshlrev_b32_e32 v44, 16, v170
	v_and_b32_e32 v45, 0xffff0000, v170
	v_pk_fma_f32 v[40:41], v[32:33], v[40:41], v[44:45]
	v_lshlrev_b32_e32 v32, 16, v167
	v_and_b32_e32 v33, 0xffff0000, v167
	v_lshlrev_b32_e32 v42, 16, v171
	v_and_b32_e32 v43, 0xffff0000, v171
	v_pk_fma_f32 v[36:37], v[36:37], v[48:49], v[50:51]
	v_pk_fma_f32 v[42:43], v[34:35], v[32:33], v[42:43]
	v_cvt_pk_bf16_f32 v32, v36, v37
	v_cvt_pk_bf16_f32 v33, v38, v39
	v_cvt_pk_bf16_f32 v34, v40, v41
	v_cvt_pk_bf16_f32 v35, v42, v43
	global_store_dwordx4 v[58:59], v[32:35], off offset:256
	s_nop 1
	v_add_u32_e32 v32, 0xa0, v140
	v_ashrrev_i32_e32 v33, 31, v32
	v_lshlrev_b64 v[34:35], 12, v[32:33]
	v_lshlrev_b64 v[36:37], 11, v[32:33]
	v_lshl_add_u64 v[32:33], s[10:11], 0, v[34:35]
	v_lshl_add_u64 v[36:37], s[12:13], 0, v[36:37]
	v_lshl_add_u64 v[40:41], v[32:33], 0, v[138:139]
	global_load_dwordx4 v[172:175], v[40:41], off offset:2048
	v_lshl_add_u64 v[42:43], v[36:37], 0, v[138:139]
	global_load_dwordx4 v[176:179], v[42:43], off
	global_load_dwordx4 v[180:183], v[40:41], off offset:2304
	global_load_dwordx4 v[184:187], v[42:43], off offset:256
	s_waitcnt vmcnt(3)
	v_lshlrev_b32_e32 v44, 16, v172
	v_and_b32_e32 v45, 0xffff0000, v172
	s_waitcnt vmcnt(2)
	v_lshlrev_b32_e32 v46, 16, v176
	v_and_b32_e32 v47, 0xffff0000, v176
	v_lshlrev_b32_e32 v32, 16, v173
	v_and_b32_e32 v33, 0xffff0000, v173
	v_lshlrev_b32_e32 v36, 16, v177
	v_and_b32_e32 v37, 0xffff0000, v177
	v_pk_fma_f32 v[30:31], v[30:31], v[32:33], v[36:37]
	v_lshlrev_b32_e32 v32, 16, v174
	v_and_b32_e32 v33, 0xffff0000, v174
	v_lshlrev_b32_e32 v36, 16, v178
	v_and_b32_e32 v37, 0xffff0000, v178
	v_pk_fma_f32 v[32:33], v[24:25], v[32:33], v[36:37]
	v_lshlrev_b32_e32 v24, 16, v175
	v_and_b32_e32 v25, 0xffff0000, v175
	v_lshlrev_b32_e32 v34, 16, v179
	v_and_b32_e32 v35, 0xffff0000, v179
	v_pk_fma_f32 v[28:29], v[28:29], v[44:45], v[46:47]
	v_pk_fma_f32 v[34:35], v[26:27], v[24:25], v[34:35]
	v_cvt_pk_bf16_f32 v24, v28, v29
	v_cvt_pk_bf16_f32 v25, v30, v31
	v_cvt_pk_bf16_f32 v26, v32, v33
	v_cvt_pk_bf16_f32 v27, v34, v35
	global_store_dwordx4 v[42:43], v[24:27], off
	s_nop 0
	s_waitcnt vmcnt(0)
	v_lshlrev_b32_e32 v32, 16, v180
	v_and_b32_e32 v33, 0xffff0000, v180
	s_waitcnt vmcnt(0)
	v_lshlrev_b32_e32 v34, 16, v184
	v_and_b32_e32 v35, 0xffff0000, v184
	v_lshlrev_b32_e32 v24, 16, v181
	v_and_b32_e32 v25, 0xffff0000, v181
	v_lshlrev_b32_e32 v28, 16, v185
	v_and_b32_e32 v29, 0xffff0000, v185
	v_pk_fma_f32 v[22:23], v[22:23], v[24:25], v[28:29]
	v_lshlrev_b32_e32 v24, 16, v182
	v_and_b32_e32 v25, 0xffff0000, v182
	v_lshlrev_b32_e32 v28, 16, v186
	v_and_b32_e32 v29, 0xffff0000, v186
	v_pk_fma_f32 v[24:25], v[16:17], v[24:25], v[28:29]
	v_lshlrev_b32_e32 v16, 16, v183
	v_and_b32_e32 v17, 0xffff0000, v183
	v_lshlrev_b32_e32 v26, 16, v187
	v_and_b32_e32 v27, 0xffff0000, v187
	v_pk_fma_f32 v[20:21], v[20:21], v[32:33], v[34:35]
	v_pk_fma_f32 v[26:27], v[18:19], v[16:17], v[26:27]
	v_cvt_pk_bf16_f32 v16, v20, v21
	v_cvt_pk_bf16_f32 v17, v22, v23
	v_cvt_pk_bf16_f32 v18, v24, v25
	v_cvt_pk_bf16_f32 v19, v26, v27
	global_store_dwordx4 v[42:43], v[16:19], off offset:256
	s_nop 1
	v_add_u32_e32 v16, 0xb0, v140
	v_ashrrev_i32_e32 v17, 31, v16
	v_lshlrev_b64 v[18:19], 12, v[16:17]
	v_lshlrev_b64 v[20:21], 11, v[16:17]
	v_lshl_add_u64 v[16:17], s[10:11], 0, v[18:19]
	v_lshl_add_u64 v[20:21], s[12:13], 0, v[20:21]
	v_lshl_add_u64 v[24:25], v[16:17], 0, v[138:139]
	global_load_dwordx4 v[188:191], v[24:25], off offset:2048
	v_lshl_add_u64 v[26:27], v[20:21], 0, v[138:139]
	global_load_dwordx4 v[192:195], v[26:27], off
	global_load_dwordx4 v[196:199], v[24:25], off offset:2304
	global_load_dwordx4 v[200:203], v[26:27], off offset:256
	s_waitcnt vmcnt(3)
	v_lshlrev_b32_e32 v28, 16, v188
	v_and_b32_e32 v29, 0xffff0000, v188
	s_waitcnt vmcnt(2)
	v_lshlrev_b32_e32 v30, 16, v192
	v_and_b32_e32 v31, 0xffff0000, v192
	v_lshlrev_b32_e32 v16, 16, v189
	v_and_b32_e32 v17, 0xffff0000, v189
	v_lshlrev_b32_e32 v20, 16, v193
	v_and_b32_e32 v21, 0xffff0000, v193
	v_pk_fma_f32 v[14:15], v[14:15], v[16:17], v[20:21]
	v_lshlrev_b32_e32 v16, 16, v190
	v_and_b32_e32 v17, 0xffff0000, v190
	v_lshlrev_b32_e32 v20, 16, v194
	v_and_b32_e32 v21, 0xffff0000, v194
	v_pk_fma_f32 v[16:17], v[8:9], v[16:17], v[20:21]
	v_lshlrev_b32_e32 v8, 16, v191
	v_and_b32_e32 v9, 0xffff0000, v191
	v_lshlrev_b32_e32 v18, 16, v195
	v_and_b32_e32 v19, 0xffff0000, v195
	v_pk_fma_f32 v[12:13], v[12:13], v[28:29], v[30:31]
	v_pk_fma_f32 v[18:19], v[10:11], v[8:9], v[18:19]
	v_cvt_pk_bf16_f32 v8, v12, v13
	v_cvt_pk_bf16_f32 v9, v14, v15
	v_cvt_pk_bf16_f32 v10, v16, v17
	v_cvt_pk_bf16_f32 v11, v18, v19
	global_store_dwordx4 v[26:27], v[8:11], off
	s_nop 0
	s_waitcnt vmcnt(0)
	v_lshlrev_b32_e32 v16, 16, v196
	v_and_b32_e32 v17, 0xffff0000, v196
	s_waitcnt vmcnt(0)
	v_lshlrev_b32_e32 v18, 16, v200
	v_and_b32_e32 v19, 0xffff0000, v200
	v_lshlrev_b32_e32 v8, 16, v197
	v_and_b32_e32 v9, 0xffff0000, v197
	v_lshlrev_b32_e32 v12, 16, v201
	v_and_b32_e32 v13, 0xffff0000, v201
	v_pk_fma_f32 v[6:7], v[6:7], v[8:9], v[12:13]
	v_lshlrev_b32_e32 v8, 16, v198
	v_and_b32_e32 v9, 0xffff0000, v198
	v_lshlrev_b32_e32 v12, 16, v202
	v_and_b32_e32 v13, 0xffff0000, v202
	v_pk_fma_f32 v[8:9], v[0:1], v[8:9], v[12:13]
	v_lshlrev_b32_e32 v0, 16, v199
	v_and_b32_e32 v1, 0xffff0000, v199
	v_lshlrev_b32_e32 v10, 16, v203
	v_and_b32_e32 v11, 0xffff0000, v203
	v_pk_fma_f32 v[4:5], v[4:5], v[16:17], v[18:19]
	v_pk_fma_f32 v[10:11], v[2:3], v[0:1], v[10:11]
	v_cvt_pk_bf16_f32 v0, v4, v5
	v_cvt_pk_bf16_f32 v1, v6, v7
	v_cvt_pk_bf16_f32 v2, v8, v9
	v_cvt_pk_bf16_f32 v3, v10, v11
	global_store_dwordx4 v[26:27], v[0:3], off offset:256
	s_cbranch_vccnz .LBB0_1321
	s_andn2_b64 vcc, exec, s[14:15]
	s_cbranch_vccnz .LBB0_1320
	s_barrier
	s_branch .LBB0_1320
